# own lean helper waves + 2x4 recurrence; helper waits s_sleep 24 after each chunk barrier so its burst does not collide with the recurrence waves' chunk start
# baseline (speedup 1.0000x reference)
.Lh_loop:
	s_sleep 24
	s_cmp_eq_u32 s12, 0
	s_cbranch_scc1 .Lh_nopost
	s_add_i32 s13, s12, 1
	s_and_b32 s13, s13, 1
	s_lshl_b32 s14, s13, 12
	v_add_u32_e32 v198, s14, v195
	s_lshl_b32 s14, s13, 7
	v_add_u32_e32 v199, s14, v196
	ds_read_b128 v[200:203], v198
	ds_read_b32 v204, v199
	s_waitcnt lgkmcnt(0)
	v_cvt_pk_bf16_f32 v200, v200, v201
	v_cvt_pk_bf16_f32 v201, v202, v203
	global_store_dwordx2 v[190:191], v[200:201], off
	s_mov_b64 s[4:5], exec
	s_and_b64 exec, exec, s[40:41]
	s_cbranch_execz .Lh_nobeta_loop
	global_store_dword v[192:193], v204, off

.Lh_nobuild:
	s_waitcnt lgkmcnt(0)
	s_barrier
	s_add_i32 s12, s12, 1
	s_cmp_lt_u32 s12, 0x41
	s_cbranch_scc1 .Lh_loop
	s_mov_b32 s13, 0
	s_and_saveexec_b64 s[6:7], s[28:29]
	s_cbranch_execz .Lh_post_skip_last
	s_lshl_b32 s14, s13, 12
	v_add_u32_e32 v198, s14, v195
	s_lshl_b32 s14, s13, 7
	v_add_u32_e32 v199, s14, v196
	ds_read_b128 v[200:203], v198
	ds_read_b32 v204, v199
	s_waitcnt lgkmcnt(0)
	v_cvt_pk_bf16_f32 v200, v200, v201
	v_cvt_pk_bf16_f32 v201, v202, v203
	global_store_dwordx2 v[190:191], v[200:201], off
	s_mov_b64 s[4:5], exec
	s_and_b64 exec, exec, s[40:41]
	s_cbranch_execz .Lh_nobeta_last
	global_store_dword v[192:193], v204, off
